# baseline (speedup 1.0000x reference)
; __device__ __forceinline__ float exp2_(float x) { return __builtin_amdgcn_exp2f(x); }
; __device__ __forceinline__ float log2_(float x) { return __builtin_amdgcn_logf(x); }
; __device__ __forceinline__ float rcp_(float x) { return __builtin_amdgcn_rcpf(x); }
; __device__ __forceinline__ float lo2f(unsigned u) { return __uint_as_float(u << 16); }
; __device__ __forceinline__ float hi2f(unsigned u) { return __uint_as_float(u & 0xffff0000u); }
; __device__ __forceinline__ void hgrn_block(const Params& p, int bh, char* smem) {
;     ...
;       float run[2] = {0.f, 0.f};
; #pragma unroll
;       for (int r = 0; r < 8; ++r) {
;         vv[r] = rv[r];
;         qv[r][0] = lo2f(rq[r]); qv[r][1] = hi2f(rq[r]);
;         float fl[2] = {lo2f(rf[r]), hi2f(rf[r])};
; #pragma unroll
;         for (int e = 0; e < 2; ++e) {
;           float sg = rcp_(1.f + exp2_(-1.4426950408889634f * fl[e]));
;           float k_ = (1.f - lb[e]) * (1.f - sg);
;           kv[r][e] = k_;
;           run[e] += log2_(1.f - k_);
;           gc[r][e] = run[e];
;         }
;       }
;       gsum[wid * 128 + d0] = run[0];
;       gsum[wid * 128 + d0 + 1] = run[1];
;       if (c + 1 < 32) {
; #pragma unroll
;         for (int r = 0; r < 8; ++r) {
;           const u16* zr = p.Z + (tokb + 64 + wid * 8 + r) * LDZ1 + h * 128 + d0;
;           rq[r] = *(const unsigned*)zr; rf[r] = *(const unsigned*)(zr + 2048); rv[r] = *(const unsigned*)(zr + 4096);
;         }
;       }
.LBB0_599:
	v_lshlrev_b32_e32 v32, 16, v111
	v_and_b32_e32 v33, 0xffff0000, v111
	v_mul_f32_e32 v32, 0xbfb8aa3b, v32
	v_mul_f32_e32 v33, 0xbfb8aa3b, v33
	v_exp_f32_e32 v32, v32
	v_exp_f32_e32 v33, v33
	v_lshlrev_b32_e32 v34, 16, v112
	s_cmp_eq_u32 s77, 1
	v_add_f32_e32 v32, 1.0, v32
	v_add_f32_e32 v33, 1.0, v33
	v_rcp_f32_e32 v32, v32
	v_rcp_f32_e32 v33, v33
	s_nop 0
	v_pk_add_f32 v[32:33], v[32:33], 1.0 op_sel_hi:[1,0] neg_lo:[1,0] neg_hi:[1,0]
	s_nop 0
	v_pk_mul_f32 v[90:91], v[56:57], v[32:33]
	v_and_b32_e32 v32, 0xffff0000, v112
	v_mul_f32_e32 v33, 0xbfb8aa3b, v34
	v_mul_f32_e32 v32, 0xbfb8aa3b, v32
	v_exp_f32_e32 v33, v33
	v_exp_f32_e32 v34, v32
	v_sub_f32_e32 v35, 1.0, v90
	v_add_f32_e32 v32, 1.0, v33
	v_add_f32_e32 v33, 1.0, v34
	v_rcp_f32_e32 v32, v32
	v_rcp_f32_e32 v33, v33
	v_log_f32_e32 v34, v35
	v_sub_f32_e32 v35, 1.0, v91
	v_log_f32_e32 v35, v35
	v_pk_add_f32 v[32:33], v[32:33], 1.0 op_sel_hi:[1,0] neg_lo:[1,0] neg_hi:[1,0]
	v_pk_add_f32 v[104:105], v[34:35], 0 op_sel_hi:[1,0]
	v_pk_mul_f32 v[86:87], v[56:57], v[32:33]
	v_lshlrev_b32_e32 v32, 16, v115
	v_and_b32_e32 v33, 0xffff0000, v115
	v_mul_f32_e32 v32, 0xbfb8aa3b, v32
	v_mul_f32_e32 v33, 0xbfb8aa3b, v33
	v_exp_f32_e32 v32, v32
	v_exp_f32_e32 v33, v33
	v_sub_f32_e32 v36, 1.0, v86
	v_sub_f32_e32 v37, 1.0, v87
	v_add_f32_e32 v32, 1.0, v32
	v_add_f32_e32 v33, 1.0, v33
	v_rcp_f32_e32 v32, v32
	v_rcp_f32_e32 v33, v33
	v_log_f32_e32 v36, v36
	v_log_f32_e32 v37, v37
	v_pk_add_f32 v[32:33], v[32:33], 1.0 op_sel_hi:[1,0] neg_lo:[1,0] neg_hi:[1,0]
	s_nop 0
	v_pk_mul_f32 v[84:85], v[56:57], v[32:33]
	v_lshlrev_b32_e32 v32, 16, v119
	v_and_b32_e32 v33, 0xffff0000, v119
	v_mul_f32_e32 v32, 0xbfb8aa3b, v32
	v_mul_f32_e32 v33, 0xbfb8aa3b, v33
	v_exp_f32_e32 v32, v32
	v_exp_f32_e32 v33, v33
	v_sub_f32_e32 v38, 1.0, v84
	v_sub_f32_e32 v39, 1.0, v85
	v_add_f32_e32 v32, 1.0, v32
	v_add_f32_e32 v33, 1.0, v33
	v_rcp_f32_e32 v32, v32
	v_rcp_f32_e32 v33, v33
	v_log_f32_e32 v38, v38
	v_log_f32_e32 v39, v39
	v_pk_add_f32 v[102:103], v[104:105], v[36:37]
	v_pk_add_f32 v[32:33], v[32:33], 1.0 op_sel_hi:[1,0] neg_lo:[1,0] neg_hi:[1,0]
	v_pk_add_f32 v[100:101], v[102:103], v[38:39]
	v_pk_mul_f32 v[82:83], v[56:57], v[32:33]
	v_lshlrev_b32_e32 v32, 16, v125
	v_and_b32_e32 v33, 0xffff0000, v125
	v_mul_f32_e32 v32, 0xbfb8aa3b, v32
	v_mul_f32_e32 v33, 0xbfb8aa3b, v33
	v_exp_f32_e32 v32, v32
	v_exp_f32_e32 v33, v33
	v_sub_f32_e32 v40, 1.0, v82
	v_sub_f32_e32 v41, 1.0, v83
	v_add_f32_e32 v32, 1.0, v32
	v_add_f32_e32 v33, 1.0, v33
	v_rcp_f32_e32 v32, v32
	v_rcp_f32_e32 v33, v33
	v_log_f32_e32 v40, v40
	v_log_f32_e32 v41, v41
	v_pk_add_f32 v[32:33], v[32:33], 1.0 op_sel_hi:[1,0] neg_lo:[1,0] neg_hi:[1,0]
	s_nop 0
	v_pk_mul_f32 v[80:81], v[56:57], v[32:33]
	v_lshlrev_b32_e32 v32, 16, v133
	v_and_b32_e32 v33, 0xffff0000, v133
	v_mul_f32_e32 v32, 0xbfb8aa3b, v32
	v_mul_f32_e32 v33, 0xbfb8aa3b, v33
	v_exp_f32_e32 v32, v32
	v_exp_f32_e32 v33, v33
	v_sub_f32_e32 v42, 1.0, v80
	v_sub_f32_e32 v43, 1.0, v81
	v_add_f32_e32 v32, 1.0, v32
	v_add_f32_e32 v33, 1.0, v33
	v_rcp_f32_e32 v32, v32
	v_rcp_f32_e32 v33, v33
	v_log_f32_e32 v42, v42
	v_log_f32_e32 v43, v43
	v_pk_add_f32 v[98:99], v[100:101], v[40:41]
	v_pk_add_f32 v[32:33], v[32:33], 1.0 op_sel_hi:[1,0] neg_lo:[1,0] neg_hi:[1,0]
	v_pk_add_f32 v[96:97], v[98:99], v[42:43]
	v_pk_mul_f32 v[78:79], v[56:57], v[32:33]
	v_lshlrev_b32_e32 v32, 16, v135
	v_and_b32_e32 v33, 0xffff0000, v135
	v_mul_f32_e32 v32, 0xbfb8aa3b, v32
	v_mul_f32_e32 v33, 0xbfb8aa3b, v33
	v_exp_f32_e32 v32, v32
	v_exp_f32_e32 v33, v33
	v_sub_f32_e32 v44, 1.0, v78
	v_sub_f32_e32 v45, 1.0, v79
	v_add_f32_e32 v32, 1.0, v32
	v_add_f32_e32 v33, 1.0, v33
	v_rcp_f32_e32 v32, v32
	v_rcp_f32_e32 v33, v33
	v_log_f32_e32 v44, v44
	v_log_f32_e32 v45, v45
	v_pk_add_f32 v[32:33], v[32:33], 1.0 op_sel_hi:[1,0] neg_lo:[1,0] neg_hi:[1,0]
	s_nop 0
	v_pk_mul_f32 v[76:77], v[56:57], v[32:33]
	v_lshlrev_b32_e32 v32, 16, v138
	v_and_b32_e32 v33, 0xffff0000, v138
	v_mul_f32_e32 v32, 0xbfb8aa3b, v32
	v_mul_f32_e32 v33, 0xbfb8aa3b, v33
	v_exp_f32_e32 v32, v32
	v_exp_f32_e32 v33, v33
	v_sub_f32_e32 v46, 1.0, v76
	v_sub_f32_e32 v47, 1.0, v77
	v_add_f32_e32 v32, 1.0, v32
	v_add_f32_e32 v33, 1.0, v33
	v_rcp_f32_e32 v32, v32
	v_rcp_f32_e32 v33, v33
	v_log_f32_e32 v46, v46
	v_log_f32_e32 v47, v47
	v_pk_add_f32 v[94:95], v[96:97], v[44:45]
	v_pk_add_f32 v[32:33], v[32:33], 1.0 op_sel_hi:[1,0] neg_lo:[1,0] neg_hi:[1,0]
	v_pk_add_f32 v[92:93], v[94:95], v[46:47]
	v_pk_mul_f32 v[74:75], v[56:57], v[32:33]
	s_nop 0
	v_sub_f32_e32 v32, 1.0, v74
	v_sub_f32_e32 v33, 1.0, v75
	v_log_f32_e32 v32, v32
	v_log_f32_e32 v33, v33
	s_nop 0
	v_pk_add_f32 v[88:89], v[92:93], v[32:33]
	ds_write_b64 v114, v[88:89]
	s_cbranch_scc1 .LBB0_601
	v_lshl_add_u64 v[32:33], v[60:61], 0, s[46:47]
	s_mov_b64 vcc, 0x101000
	s_mov_b64 s[52:53], 0x1000
	v_lshl_add_u64 v[34:35], v[32:33], 0, vcc
	s_mov_b64 vcc, 0x3000
	global_load_dword v134, v[34:35], off offset:-4096
	global_load_dword v111, v[34:35], off
	v_lshl_add_u64 v[34:35], v[34:35], 0, s[52:53]
	global_load_dword v136, v[34:35], off
	v_lshl_add_u64 v[34:35], v[34:35], 0, vcc
	global_load_dword v137, v[34:35], off offset:-4096
	global_load_dword v112, v[34:35], off
	v_lshl_add_u64 v[34:35], v[34:35], 0, s[52:53]
	global_load_dword v139, v[34:35], off
	v_lshl_add_u64 v[34:35], v[34:35], 0, vcc
	global_load_dword v140, v[34:35], off offset:-4096
	global_load_dword v115, v[34:35], off
	v_lshl_add_u64 v[34:35], v[34:35], 0, s[52:53]
	global_load_dword v141, v[34:35], off
	v_lshl_add_u64 v[34:35], v[34:35], 0, vcc
	global_load_dword v142, v[34:35], off offset:-4096
	global_load_dword v119, v[34:35], off
	v_lshl_add_u64 v[34:35], v[34:35], 0, s[52:53]
	global_load_dword v143, v[34:35], off
	v_lshl_add_u64 v[34:35], v[34:35], 0, vcc
	global_load_dword v144, v[34:35], off offset:-4096
	global_load_dword v125, v[34:35], off
	v_lshl_add_u64 v[34:35], v[34:35], 0, s[52:53]
	global_load_dword v145, v[34:35], off
	v_lshl_add_u64 v[34:35], v[34:35], 0, vcc
	global_load_dword v146, v[34:35], off offset:-4096
	global_load_dword v133, v[34:35], off
	v_lshl_add_u64 v[34:35], v[34:35], 0, s[52:53]
	global_load_dword v147, v[34:35], off
	v_lshl_add_u64 v[34:35], v[34:35], 0, vcc
	global_load_dword v148, v[34:35], off offset:-4096
	global_load_dword v135, v[34:35], off
	v_lshl_add_u64 v[34:35], v[34:35], 0, s[52:53]
	global_load_dword v149, v[34:35], off
	v_lshl_add_u64 v[34:35], v[34:35], 0, vcc
	global_load_dword v150, v[34:35], off offset:-4096
	global_load_dword v138, v[34:35], off
	v_lshl_add_u64 v[34:35], v[34:35], 0, s[52:53]
	global_load_dword v151, v[34:35], off
